# attention non-loop QK / final PV drain blocks: reads pipelined through the fragment ring with counted waits
# baseline (speedup 1.0000x reference)
.LBB0_503:
	v_exp_f32_e32 v46, v46
	v_exp_f32_e32 v47, v47
	s_nop 0
	v_exp_f32_e32 v62, v30
	v_exp_f32_e32 v63, v31
	v_exp_f32_e32 v32, v32
	v_exp_f32_e32 v33, v33
	v_exp_f32_e32 v34, v34
	v_exp_f32_e32 v35, v35
	v_exp_f32_e32 v36, v36
	v_exp_f32_e32 v37, v37
	v_exp_f32_e32 v38, v38
	v_exp_f32_e32 v39, v39
	v_exp_f32_e32 v40, v40
	v_exp_f32_e32 v41, v41
	v_exp_f32_e32 v42, v42
	v_exp_f32_e32 v43, v43
	v_exp_f32_e32 v44, v44
	v_exp_f32_e32 v45, v45
	v_exp_f32_e32 v48, v16
	v_exp_f32_e32 v49, v17
	v_exp_f32_e32 v50, v18
	v_exp_f32_e32 v51, v19
	v_exp_f32_e32 v52, v20
	v_exp_f32_e32 v53, v21
	v_exp_f32_e32 v54, v22
	v_exp_f32_e32 v55, v23
	v_exp_f32_e32 v56, v24
	v_exp_f32_e32 v57, v25
	v_exp_f32_e32 v58, v26
	v_exp_f32_e32 v59, v27
	v_exp_f32_e32 v60, v28
	v_exp_f32_e32 v61, v29
	v_mov_b64_e32 v[94:95], v[62:63]
	v_mov_b64_e32 v[110:111], v[46:47]
	s_andn2_b64 vcc, exec, s[76:77]
	v_mov_b64_e32 v[92:93], v[60:61]
	v_mov_b64_e32 v[90:91], v[58:59]
	v_mov_b64_e32 v[88:89], v[56:57]
	v_mov_b64_e32 v[86:87], v[54:55]
	v_mov_b64_e32 v[84:85], v[52:53]
	v_mov_b64_e32 v[82:83], v[50:51]
	v_mov_b64_e32 v[80:81], v[48:49]
	v_mov_b64_e32 v[108:109], v[44:45]
	v_mov_b64_e32 v[106:107], v[42:43]
	v_mov_b64_e32 v[104:105], v[40:41]
	v_mov_b64_e32 v[102:103], v[38:39]
	v_mov_b64_e32 v[100:101], v[36:37]
	v_mov_b64_e32 v[98:99], v[34:35]
	v_mov_b64_e32 v[96:97], v[32:33]
	s_cbranch_vccnz .LBB0_505
	ds_read_b128 v[222:225], v208 offset:9216
	ds_read_b128 v[226:229], v208 offset:13824
	ds_read_b128 v[230:233], v208 offset:9248
	ds_read_b128 v[234:237], v208 offset:13856
	ds_read_b128 v[238:241], v208 offset:9280
	ds_read_b128 v[242:245], v208 offset:13888
	ds_read_b128 v[246:249], v208 offset:9312
	ds_read_b128 v[250:253], v208 offset:13920
	s_waitcnt lgkmcnt(7)
	v_mfma_f32_32x32x16_bf16 v[96:111], v[222:225], v[124:127], 0
	s_waitcnt lgkmcnt(6)
	v_mfma_f32_32x32x16_bf16 v[80:95], v[226:229], v[124:127], 0
	s_waitcnt lgkmcnt(5)
	v_mfma_f32_32x32x16_bf16 v[96:111], v[230:233], v[120:123], v[96:111]
	s_waitcnt lgkmcnt(4)
	v_mfma_f32_32x32x16_bf16 v[80:95], v[234:237], v[120:123], v[80:95]
	s_waitcnt lgkmcnt(3)
	v_mfma_f32_32x32x16_bf16 v[96:111], v[238:241], v[116:119], v[96:111]
	s_waitcnt lgkmcnt(2)
	v_mfma_f32_32x32x16_bf16 v[80:95], v[242:245], v[116:119], v[80:95]
	s_waitcnt lgkmcnt(1)
	v_mfma_f32_32x32x16_bf16 v[96:111], v[246:249], v[112:115], v[96:111]
	s_waitcnt lgkmcnt(0)
	v_mfma_f32_32x32x16_bf16 v[80:95], v[250:253], v[112:115], v[80:95]

.LBB0_513:
	s_xor_b64 s[6:7], s[72:73], -1
	s_mov_b64 s[72:73], -1
	s_and_b64 vcc, exec, s[82:83]
	s_cbranch_vccz .LBB0_515
	s_mov_b64 s[72:73], 0
	ds_read_b128 v[222:225], v208 offset:36864
	ds_read_b128 v[226:229], v208 offset:41472
	ds_read_b128 v[230:233], v208 offset:46080
	ds_read_b128 v[234:237], v208 offset:50688
	ds_read_b128 v[238:241], v208 offset:36896
	ds_read_b128 v[242:245], v208 offset:41504
	ds_read_b128 v[246:249], v208 offset:46112
	ds_read_b128 v[250:253], v208 offset:50720
	s_waitcnt lgkmcnt(7)
	v_mfma_f32_32x32x16_bf16 v[128:143], v[222:225], v[160:163], v[32:47]
	ds_read_b128 v[222:225], v208 offset:36928
	s_waitcnt lgkmcnt(7)
	v_mfma_f32_32x32x16_bf16 v[112:127], v[226:229], v[160:163], v[64:79]
	ds_read_b128 v[226:229], v208 offset:41536
	s_waitcnt lgkmcnt(7)
	v_mfma_f32_32x32x16_bf16 v[96:111], v[230:233], v[160:163], v[48:63]
	ds_read_b128 v[230:233], v208 offset:46144
	s_waitcnt lgkmcnt(7)
	v_mfma_f32_32x32x16_bf16 v[80:95], v[234:237], v[160:163], v[16:31]
	ds_read_b128 v[234:237], v208 offset:50752
	s_waitcnt lgkmcnt(7)
	v_mfma_f32_32x32x16_bf16 v[128:143], v[238:241], v[148:151], v[128:143]
	ds_read_b128 v[238:241], v208 offset:36960
	s_waitcnt lgkmcnt(7)
	v_mfma_f32_32x32x16_bf16 v[112:127], v[242:245], v[148:151], v[112:127]
	ds_read_b128 v[242:245], v208 offset:41568
	s_waitcnt lgkmcnt(7)
	v_mfma_f32_32x32x16_bf16 v[96:111], v[246:249], v[148:151], v[96:111]
	ds_read_b128 v[246:249], v208 offset:46176
	s_waitcnt lgkmcnt(7)
	v_mfma_f32_32x32x16_bf16 v[80:95], v[250:253], v[148:151], v[80:95]
	ds_read_b128 v[250:253], v208 offset:50784
	s_waitcnt lgkmcnt(7)
	v_mfma_f32_32x32x16_bf16 v[128:143], v[222:225], v[152:155], v[128:143]
	s_waitcnt lgkmcnt(6)
	v_mfma_f32_32x32x16_bf16 v[112:127], v[226:229], v[152:155], v[112:127]
	s_waitcnt lgkmcnt(5)
	v_mfma_f32_32x32x16_bf16 v[96:111], v[230:233], v[152:155], v[96:111]
	s_waitcnt lgkmcnt(4)
	v_mfma_f32_32x32x16_bf16 v[80:95], v[234:237], v[152:155], v[80:95]
	s_waitcnt lgkmcnt(3)
	v_mfma_f32_32x32x16_bf16 v[128:143], v[238:241], v[156:159], v[128:143]
	s_waitcnt lgkmcnt(2)
	v_mfma_f32_32x32x16_bf16 v[112:127], v[242:245], v[156:159], v[112:127]
	s_waitcnt lgkmcnt(1)
	v_mfma_f32_32x32x16_bf16 v[96:111], v[246:249], v[156:159], v[96:111]
	s_waitcnt lgkmcnt(0)
	v_mfma_f32_32x32x16_bf16 v[80:95], v[250:253], v[156:159], v[80:95]

.LBB0_537:
	v_exp_f32_e32 v46, v46
	v_exp_f32_e32 v47, v47
	s_nop 0
	v_exp_f32_e32 v62, v30
	v_exp_f32_e32 v63, v31
	v_exp_f32_e32 v32, v32
	v_exp_f32_e32 v33, v33
	v_exp_f32_e32 v34, v34
	v_exp_f32_e32 v35, v35
	v_exp_f32_e32 v36, v36
	v_exp_f32_e32 v37, v37
	v_exp_f32_e32 v38, v38
	v_exp_f32_e32 v39, v39
	v_exp_f32_e32 v40, v40
	v_exp_f32_e32 v41, v41
	v_exp_f32_e32 v42, v42
	v_exp_f32_e32 v43, v43
	v_exp_f32_e32 v44, v44
	v_exp_f32_e32 v45, v45
	v_exp_f32_e32 v48, v16
	v_exp_f32_e32 v49, v17
	v_exp_f32_e32 v50, v18
	v_exp_f32_e32 v51, v19
	v_exp_f32_e32 v52, v20
	v_exp_f32_e32 v53, v21
	v_exp_f32_e32 v54, v22
	v_exp_f32_e32 v55, v23
	v_exp_f32_e32 v56, v24
	v_exp_f32_e32 v57, v25
	v_exp_f32_e32 v58, v26
	v_exp_f32_e32 v59, v27
	v_exp_f32_e32 v60, v28
	v_exp_f32_e32 v61, v29
	v_mov_b64_e32 v[94:95], v[62:63]
	v_mov_b64_e32 v[110:111], v[46:47]
	s_andn2_b64 vcc, exec, s[74:75]
	v_mov_b64_e32 v[92:93], v[60:61]
	v_mov_b64_e32 v[90:91], v[58:59]
	v_mov_b64_e32 v[88:89], v[56:57]
	v_mov_b64_e32 v[86:87], v[54:55]
	v_mov_b64_e32 v[84:85], v[52:53]
	v_mov_b64_e32 v[82:83], v[50:51]
	v_mov_b64_e32 v[80:81], v[48:49]
	v_mov_b64_e32 v[108:109], v[44:45]
	v_mov_b64_e32 v[106:107], v[42:43]
	v_mov_b64_e32 v[104:105], v[40:41]
	v_mov_b64_e32 v[102:103], v[38:39]
	v_mov_b64_e32 v[100:101], v[36:37]
	v_mov_b64_e32 v[98:99], v[34:35]
	v_mov_b64_e32 v[96:97], v[32:33]
	s_cbranch_vccnz .LBB0_539
	ds_read_b128 v[222:225], v208 offset:9216
	ds_read_b128 v[226:229], v208 offset:13824
	ds_read_b128 v[230:233], v208 offset:9248
	ds_read_b128 v[234:237], v208 offset:13856
	ds_read_b128 v[238:241], v208 offset:9280
	ds_read_b128 v[242:245], v208 offset:13888
	ds_read_b128 v[246:249], v208 offset:9312
	ds_read_b128 v[250:253], v208 offset:13920
	s_waitcnt lgkmcnt(7)
	v_mfma_f32_32x32x16_bf16 v[96:111], v[222:225], v[124:127], 0
	s_waitcnt lgkmcnt(6)
	v_mfma_f32_32x32x16_bf16 v[80:95], v[226:229], v[124:127], 0
	s_waitcnt lgkmcnt(5)
	v_mfma_f32_32x32x16_bf16 v[96:111], v[230:233], v[120:123], v[96:111]
	s_waitcnt lgkmcnt(4)
	v_mfma_f32_32x32x16_bf16 v[80:95], v[234:237], v[120:123], v[80:95]
	s_waitcnt lgkmcnt(3)
	v_mfma_f32_32x32x16_bf16 v[96:111], v[238:241], v[116:119], v[96:111]
	s_waitcnt lgkmcnt(2)
	v_mfma_f32_32x32x16_bf16 v[80:95], v[242:245], v[116:119], v[80:95]
	s_waitcnt lgkmcnt(1)
	v_mfma_f32_32x32x16_bf16 v[96:111], v[246:249], v[112:115], v[96:111]
	s_waitcnt lgkmcnt(0)
	v_mfma_f32_32x32x16_bf16 v[80:95], v[250:253], v[112:115], v[80:95]

.LBB0_547:
	s_xor_b64 s[6:7], s[72:73], -1
	s_mov_b64 s[72:73], -1
	s_and_b64 vcc, exec, s[78:79]
	s_cbranch_vccz .LBB0_549
	s_mov_b64 s[72:73], 0
	ds_read_b128 v[222:225], v208 offset:36864
	ds_read_b128 v[226:229], v208 offset:41472
	ds_read_b128 v[230:233], v208 offset:46080
	ds_read_b128 v[234:237], v208 offset:50688
	ds_read_b128 v[238:241], v208 offset:36896
	ds_read_b128 v[242:245], v208 offset:41504
	ds_read_b128 v[246:249], v208 offset:46112
	ds_read_b128 v[250:253], v208 offset:50720
	s_waitcnt lgkmcnt(7)
	v_mfma_f32_32x32x16_bf16 v[128:143], v[222:225], v[160:163], v[32:47]
	ds_read_b128 v[222:225], v208 offset:36928
	s_waitcnt lgkmcnt(7)
	v_mfma_f32_32x32x16_bf16 v[112:127], v[226:229], v[160:163], v[64:79]
	ds_read_b128 v[226:229], v208 offset:41536
	s_waitcnt lgkmcnt(7)
	v_mfma_f32_32x32x16_bf16 v[96:111], v[230:233], v[160:163], v[48:63]
	ds_read_b128 v[230:233], v208 offset:46144
	s_waitcnt lgkmcnt(7)
	v_mfma_f32_32x32x16_bf16 v[80:95], v[234:237], v[160:163], v[16:31]
	ds_read_b128 v[234:237], v208 offset:50752
	s_waitcnt lgkmcnt(7)
	v_mfma_f32_32x32x16_bf16 v[128:143], v[238:241], v[148:151], v[128:143]
	ds_read_b128 v[238:241], v208 offset:36960
	s_waitcnt lgkmcnt(7)
	v_mfma_f32_32x32x16_bf16 v[112:127], v[242:245], v[148:151], v[112:127]
	ds_read_b128 v[242:245], v208 offset:41568
	s_waitcnt lgkmcnt(7)
	v_mfma_f32_32x32x16_bf16 v[96:111], v[246:249], v[148:151], v[96:111]
	ds_read_b128 v[246:249], v208 offset:46176
	s_waitcnt lgkmcnt(7)
	v_mfma_f32_32x32x16_bf16 v[80:95], v[250:253], v[148:151], v[80:95]
	ds_read_b128 v[250:253], v208 offset:50784
	s_waitcnt lgkmcnt(7)
	v_mfma_f32_32x32x16_bf16 v[128:143], v[222:225], v[152:155], v[128:143]
	s_waitcnt lgkmcnt(6)
	v_mfma_f32_32x32x16_bf16 v[112:127], v[226:229], v[152:155], v[112:127]
	s_waitcnt lgkmcnt(5)
	v_mfma_f32_32x32x16_bf16 v[96:111], v[230:233], v[152:155], v[96:111]
	s_waitcnt lgkmcnt(4)
	v_mfma_f32_32x32x16_bf16 v[80:95], v[234:237], v[152:155], v[80:95]
	s_waitcnt lgkmcnt(3)
	v_mfma_f32_32x32x16_bf16 v[128:143], v[238:241], v[156:159], v[128:143]
	s_waitcnt lgkmcnt(2)
	v_mfma_f32_32x32x16_bf16 v[112:127], v[242:245], v[156:159], v[112:127]
	s_waitcnt lgkmcnt(1)
	v_mfma_f32_32x32x16_bf16 v[96:111], v[246:249], v[156:159], v[96:111]
	s_waitcnt lgkmcnt(0)
	v_mfma_f32_32x32x16_bf16 v[80:95], v[250:253], v[156:159], v[80:95]
